# e26: e25 plus nt on P11 fnet_finish's full-line Y1 stores (written once, read by P12 a phase later)
# speedup vs baseline: 1.0070x; 1.0010x over previous
.LBB0_1649:
	s_waitcnt vmcnt(19)
	v_lshlrev_b32_e32 v1, 16, v94
	v_lshlrev_b32_e32 v106, 16, v82
	v_and_b32_e32 v94, 0xffff0000, v94
	v_and_b32_e32 v107, 0xffff0000, v82
	v_sub_f32_e32 v82, v106, v1
	v_lshlrev_b32_e32 v108, 16, v90
	v_mul_f32_e32 v82, v82, v108
	v_sub_f32_e32 v108, v107, v94
	v_and_b32_e32 v90, 0xffff0000, v90
	v_mul_f32_e32 v90, v108, v90
	v_cvt_pk_bf16_f32 v82, v82, v90
	v_add_f32_e32 v1, v1, v106
	v_lshlrev_b32_e32 v90, 16, v86
	v_mul_f32_e32 v1, v1, v90
	v_add_f32_e32 v90, v94, v107
	v_and_b32_e32 v86, 0xffff0000, v86
	v_mul_f32_e32 v86, v90, v86
	v_cvt_pk_bf16_f32 v86, v1, v86
	v_lshlrev_b32_e32 v1, 16, v95
	v_lshlrev_b32_e32 v90, 16, v83
	v_and_b32_e32 v94, 0xffff0000, v95
	v_and_b32_e32 v95, 0xffff0000, v83
	v_sub_f32_e32 v83, v90, v1
	v_add_f32_e32 v1, v1, v90
	v_lshlrev_b32_e32 v90, 16, v87
	v_lshlrev_b32_e32 v106, 16, v91
	v_mul_f32_e32 v1, v1, v90
	v_add_f32_e32 v90, v94, v95
	v_and_b32_e32 v87, 0xffff0000, v87
	v_mul_f32_e32 v83, v83, v106
	v_sub_f32_e32 v106, v95, v94
	v_and_b32_e32 v91, 0xffff0000, v91
	v_mul_f32_e32 v87, v90, v87
	v_mul_f32_e32 v91, v106, v91
	v_cvt_pk_bf16_f32 v83, v83, v91
	v_cvt_pk_bf16_f32 v87, v1, v87
	v_lshlrev_b32_e32 v1, 16, v96
	v_lshlrev_b32_e32 v90, 16, v84
	v_and_b32_e32 v91, 0xffff0000, v96
	v_and_b32_e32 v94, 0xffff0000, v84
	v_sub_f32_e32 v84, v90, v1
	v_add_f32_e32 v1, v1, v90
	v_lshlrev_b32_e32 v90, 16, v88
	v_lshlrev_b32_e32 v95, 16, v92
	v_mul_f32_e32 v1, v1, v90
	v_add_f32_e32 v90, v91, v94
	v_and_b32_e32 v88, 0xffff0000, v88
	v_mul_f32_e32 v84, v84, v95
	v_sub_f32_e32 v95, v94, v91
	v_and_b32_e32 v92, 0xffff0000, v92
	v_mul_f32_e32 v88, v90, v88
	s_add_u32 s0, s6, s28
	v_mul_f32_e32 v92, v95, v92
	v_cvt_pk_bf16_f32 v84, v84, v92
	v_cvt_pk_bf16_f32 v88, v1, v88
	v_lshlrev_b32_e32 v1, 16, v97
	v_lshlrev_b32_e32 v90, 16, v85
	s_addc_u32 s1, s7, s29
	v_and_b32_e32 v91, 0xffff0000, v97
	v_and_b32_e32 v92, 0xffff0000, v85
	v_sub_f32_e32 v85, v90, v1
	v_add_f32_e32 v1, v1, v90
	v_lshlrev_b32_e32 v90, 16, v89
	v_lshl_add_u64 v[98:99], s[0:1], 0, v[128:129]
	s_add_u32 s0, s6, s30
	v_mul_f32_e32 v1, v1, v90
	v_add_f32_e32 v90, v91, v92
	v_and_b32_e32 v89, 0xffff0000, v89
	s_addc_u32 s1, s7, s31
	v_lshlrev_b32_e32 v94, 16, v93
	v_mul_f32_e32 v89, v90, v89
	v_add_co_u32_e32 v90, vcc, s41, v98
	v_lshl_add_u64 v[102:103], s[0:1], 0, v[128:129]
	v_mul_f32_e32 v85, v85, v94
	v_sub_f32_e32 v94, v92, v91
	v_and_b32_e32 v93, 0xffff0000, v93
	v_addc_co_u32_e32 v91, vcc, 0, v99, vcc
	v_mul_f32_e32 v93, v94, v93
	v_cvt_pk_bf16_f32 v85, v85, v93
	v_cvt_pk_bf16_f32 v89, v1, v89
	global_store_dwordx4 v[90:91], v[82:85], off offset:2048 nt
	v_lshlrev_b32_e32 v1, 16, v78
	v_and_b32_e32 v78, 0xffff0000, v78
	v_add_co_u32_e32 v82, vcc, s41, v102
	v_lshlrev_b32_e32 v84, 16, v74
	s_nop 0
	v_addc_co_u32_e32 v83, vcc, 0, v103, vcc
	global_store_dwordx4 v[82:83], v[86:89], off offset:2048 nt
	v_lshlrev_b32_e32 v82, 16, v66
	v_and_b32_e32 v83, 0xffff0000, v66
	v_sub_f32_e32 v66, v82, v1
	v_mul_f32_e32 v66, v66, v84
	v_sub_f32_e32 v84, v83, v78
	v_and_b32_e32 v74, 0xffff0000, v74
	v_mul_f32_e32 v74, v84, v74
	v_cvt_pk_bf16_f32 v66, v66, v74
	v_add_f32_e32 v1, v1, v82
	s_waitcnt vmcnt(20)
	v_lshlrev_b32_e32 v74, 16, v70
	v_mul_f32_e32 v1, v1, v74
	v_add_f32_e32 v74, v78, v83
	v_and_b32_e32 v70, 0xffff0000, v70
	v_mul_f32_e32 v70, v74, v70
	v_cvt_pk_bf16_f32 v70, v1, v70
	v_lshlrev_b32_e32 v1, 16, v79
	v_lshlrev_b32_e32 v74, 16, v67
	v_and_b32_e32 v78, 0xffff0000, v79
	v_and_b32_e32 v79, 0xffff0000, v67
	v_sub_f32_e32 v67, v74, v1
	v_add_f32_e32 v1, v1, v74
	v_lshlrev_b32_e32 v74, 16, v71
	v_lshlrev_b32_e32 v82, 16, v75
	v_mul_f32_e32 v1, v1, v74
	v_add_f32_e32 v74, v78, v79
	v_and_b32_e32 v71, 0xffff0000, v71
	v_mul_f32_e32 v67, v67, v82
	v_sub_f32_e32 v82, v79, v78
	v_and_b32_e32 v75, 0xffff0000, v75
	v_mul_f32_e32 v71, v74, v71
	v_mul_f32_e32 v75, v82, v75
	v_cvt_pk_bf16_f32 v67, v67, v75
	v_cvt_pk_bf16_f32 v71, v1, v71
	v_lshlrev_b32_e32 v1, 16, v80
	v_lshlrev_b32_e32 v74, 16, v68
	v_and_b32_e32 v75, 0xffff0000, v80
	v_and_b32_e32 v78, 0xffff0000, v68
	v_sub_f32_e32 v68, v74, v1
	v_add_f32_e32 v1, v1, v74
	v_lshlrev_b32_e32 v74, 16, v72
	v_lshlrev_b32_e32 v79, 16, v76
	v_mul_f32_e32 v1, v1, v74
	v_add_f32_e32 v74, v75, v78
	v_and_b32_e32 v72, 0xffff0000, v72
	v_mul_f32_e32 v68, v68, v79
	v_sub_f32_e32 v79, v78, v75
	v_and_b32_e32 v76, 0xffff0000, v76
	v_mul_f32_e32 v72, v74, v72
	v_mul_f32_e32 v76, v79, v76
	v_cvt_pk_bf16_f32 v68, v68, v76
	v_cvt_pk_bf16_f32 v72, v1, v72
	v_lshlrev_b32_e32 v1, 16, v81
	v_lshlrev_b32_e32 v74, 16, v69
	v_and_b32_e32 v75, 0xffff0000, v81
	v_and_b32_e32 v76, 0xffff0000, v69
	v_sub_f32_e32 v69, v74, v1
	v_add_f32_e32 v1, v1, v74
	v_lshlrev_b32_e32 v74, 16, v73
	v_lshlrev_b32_e32 v78, 16, v77
	v_mul_f32_e32 v1, v1, v74
	v_add_f32_e32 v74, v75, v76
	v_and_b32_e32 v73, 0xffff0000, v73
	v_mul_f32_e32 v69, v69, v78
	v_sub_f32_e32 v78, v76, v75
	v_and_b32_e32 v77, 0xffff0000, v77
	v_mul_f32_e32 v73, v74, v73
	v_mul_f32_e32 v77, v78, v77
	v_cvt_pk_bf16_f32 v69, v69, v77
	v_cvt_pk_bf16_f32 v73, v1, v73
	s_waitcnt vmcnt(13)
	v_lshlrev_b32_e32 v1, 16, v62
	v_lshlrev_b32_e32 v74, 16, v50
	v_and_b32_e32 v62, 0xffff0000, v62
	v_and_b32_e32 v75, 0xffff0000, v50
	v_sub_f32_e32 v50, v74, v1
	v_lshlrev_b32_e32 v76, 16, v58
	v_mul_f32_e32 v50, v50, v76
	v_sub_f32_e32 v76, v75, v62
	v_and_b32_e32 v58, 0xffff0000, v58
	v_lshl_add_u64 v[100:101], v[98:99], 0, s[16:17]
	v_mul_f32_e32 v58, v76, v58
	v_lshl_add_u64 v[104:105], v[102:103], 0, s[16:17]
	global_store_dwordx4 v[100:101], v[66:69], off offset:16 nt
	global_store_dwordx4 v[104:105], v[70:73], off offset:16 nt
	v_cvt_pk_bf16_f32 v50, v50, v58
	v_add_f32_e32 v1, v1, v74
	v_lshlrev_b32_e32 v58, 16, v54
	v_mul_f32_e32 v1, v1, v58
	v_add_f32_e32 v58, v62, v75
	v_and_b32_e32 v54, 0xffff0000, v54
	v_mul_f32_e32 v54, v58, v54
	v_cvt_pk_bf16_f32 v54, v1, v54
	v_lshlrev_b32_e32 v1, 16, v63
	v_lshlrev_b32_e32 v58, 16, v51
	v_and_b32_e32 v62, 0xffff0000, v63
	v_and_b32_e32 v63, 0xffff0000, v51
	v_sub_f32_e32 v51, v58, v1
	v_add_f32_e32 v1, v1, v58
	v_lshlrev_b32_e32 v58, 16, v55
	v_lshlrev_b32_e32 v74, 16, v59
	v_mul_f32_e32 v1, v1, v58
	v_add_f32_e32 v58, v62, v63
	v_and_b32_e32 v55, 0xffff0000, v55
	v_mul_f32_e32 v51, v51, v74
	v_sub_f32_e32 v74, v63, v62
	v_and_b32_e32 v59, 0xffff0000, v59
	v_mul_f32_e32 v55, v58, v55
	v_mul_f32_e32 v59, v74, v59
	v_cvt_pk_bf16_f32 v51, v51, v59
	v_cvt_pk_bf16_f32 v55, v1, v55
	v_lshlrev_b32_e32 v1, 16, v64
	v_lshlrev_b32_e32 v58, 16, v52
	v_and_b32_e32 v59, 0xffff0000, v64
	v_and_b32_e32 v62, 0xffff0000, v52
	v_sub_f32_e32 v52, v58, v1
	v_add_f32_e32 v1, v1, v58
	v_lshlrev_b32_e32 v58, 16, v56
	v_lshlrev_b32_e32 v63, 16, v60
	v_mul_f32_e32 v1, v1, v58
	v_add_f32_e32 v58, v59, v62
	v_and_b32_e32 v56, 0xffff0000, v56
	v_mul_f32_e32 v52, v52, v63
	v_sub_f32_e32 v63, v62, v59
	v_and_b32_e32 v60, 0xffff0000, v60
	v_mul_f32_e32 v56, v58, v56
	s_add_u32 s0, s6, s22
	v_mul_f32_e32 v60, v63, v60
	v_cvt_pk_bf16_f32 v52, v52, v60
	v_cvt_pk_bf16_f32 v56, v1, v56
	v_lshlrev_b32_e32 v1, 16, v65
	v_lshlrev_b32_e32 v58, 16, v53
	s_addc_u32 s1, s7, s23
	v_and_b32_e32 v59, 0xffff0000, v65
	v_and_b32_e32 v60, 0xffff0000, v53
	v_sub_f32_e32 v53, v58, v1
	v_add_f32_e32 v1, v1, v58
	v_lshlrev_b32_e32 v58, 16, v57
	v_lshl_add_u64 v[66:67], s[0:1], 0, v[128:129]
	s_add_u32 s0, s6, s24
	v_mul_f32_e32 v1, v1, v58
	v_add_f32_e32 v58, v59, v60
	v_and_b32_e32 v57, 0xffff0000, v57
	s_addc_u32 s1, s7, s25
	v_lshlrev_b32_e32 v62, 16, v61
	v_mul_f32_e32 v57, v58, v57
	v_add_co_u32_e32 v58, vcc, s41, v66
	v_lshl_add_u64 v[70:71], s[0:1], 0, v[128:129]
	v_mul_f32_e32 v53, v53, v62
	v_sub_f32_e32 v62, v60, v59
	v_and_b32_e32 v61, 0xffff0000, v61
	v_addc_co_u32_e32 v59, vcc, 0, v67, vcc
	v_mul_f32_e32 v61, v62, v61
	v_cvt_pk_bf16_f32 v53, v53, v61
	v_cvt_pk_bf16_f32 v57, v1, v57
	global_store_dwordx4 v[58:59], v[50:53], off offset:2048 nt
	v_lshlrev_b32_e32 v1, 16, v46
	v_and_b32_e32 v46, 0xffff0000, v46
	v_add_co_u32_e32 v50, vcc, s41, v70
	v_lshlrev_b32_e32 v52, 16, v42
	s_nop 0
	v_addc_co_u32_e32 v51, vcc, 0, v71, vcc
	global_store_dwordx4 v[50:51], v[54:57], off offset:2048 nt
	v_lshlrev_b32_e32 v50, 16, v34
	v_and_b32_e32 v51, 0xffff0000, v34
	v_sub_f32_e32 v34, v50, v1
	v_mul_f32_e32 v34, v34, v52
	v_sub_f32_e32 v52, v51, v46
	v_and_b32_e32 v42, 0xffff0000, v42
	v_mul_f32_e32 v42, v52, v42
	v_cvt_pk_bf16_f32 v34, v34, v42
	v_add_f32_e32 v1, v1, v50
	s_waitcnt vmcnt(16)
	v_lshlrev_b32_e32 v42, 16, v38
	v_mul_f32_e32 v1, v1, v42
	v_add_f32_e32 v42, v46, v51
	v_and_b32_e32 v38, 0xffff0000, v38
	v_mul_f32_e32 v38, v42, v38
	v_cvt_pk_bf16_f32 v38, v1, v38
	v_lshlrev_b32_e32 v1, 16, v47
	v_lshlrev_b32_e32 v42, 16, v35
	v_and_b32_e32 v46, 0xffff0000, v47
	v_and_b32_e32 v47, 0xffff0000, v35
	v_sub_f32_e32 v35, v42, v1
	v_add_f32_e32 v1, v1, v42
	v_lshlrev_b32_e32 v42, 16, v39
	v_lshlrev_b32_e32 v50, 16, v43
	v_mul_f32_e32 v1, v1, v42
	v_add_f32_e32 v42, v46, v47
	v_and_b32_e32 v39, 0xffff0000, v39
	v_mul_f32_e32 v35, v35, v50
	v_sub_f32_e32 v50, v47, v46
	v_and_b32_e32 v43, 0xffff0000, v43
	v_mul_f32_e32 v39, v42, v39
	v_mul_f32_e32 v43, v50, v43
	v_cvt_pk_bf16_f32 v35, v35, v43
	v_cvt_pk_bf16_f32 v39, v1, v39
	v_lshlrev_b32_e32 v1, 16, v48
	v_lshlrev_b32_e32 v42, 16, v36
	v_and_b32_e32 v43, 0xffff0000, v48
	v_and_b32_e32 v46, 0xffff0000, v36
	v_sub_f32_e32 v36, v42, v1
	v_add_f32_e32 v1, v1, v42
	v_lshlrev_b32_e32 v42, 16, v40
	v_lshlrev_b32_e32 v47, 16, v44
	v_mul_f32_e32 v1, v1, v42
	v_add_f32_e32 v42, v43, v46
	v_and_b32_e32 v40, 0xffff0000, v40
	v_mul_f32_e32 v36, v36, v47
	v_sub_f32_e32 v47, v46, v43
	v_and_b32_e32 v44, 0xffff0000, v44
	v_mul_f32_e32 v40, v42, v40
	v_mul_f32_e32 v44, v47, v44
	v_cvt_pk_bf16_f32 v36, v36, v44
	v_cvt_pk_bf16_f32 v40, v1, v40
	v_lshlrev_b32_e32 v1, 16, v49
	v_lshlrev_b32_e32 v42, 16, v37
	v_and_b32_e32 v43, 0xffff0000, v49
	v_and_b32_e32 v44, 0xffff0000, v37
	v_sub_f32_e32 v37, v42, v1
	v_add_f32_e32 v1, v1, v42
	v_lshlrev_b32_e32 v42, 16, v41
	v_lshlrev_b32_e32 v46, 16, v45
	v_mul_f32_e32 v1, v1, v42
	v_add_f32_e32 v42, v43, v44
	v_and_b32_e32 v41, 0xffff0000, v41
	v_mul_f32_e32 v37, v37, v46
	v_sub_f32_e32 v46, v44, v43
	v_and_b32_e32 v45, 0xffff0000, v45
	v_mul_f32_e32 v41, v42, v41
	v_mul_f32_e32 v45, v46, v45
	v_cvt_pk_bf16_f32 v37, v37, v45
	v_cvt_pk_bf16_f32 v41, v1, v41
	s_waitcnt vmcnt(9)
	v_lshlrev_b32_e32 v1, 16, v30
	v_lshlrev_b32_e32 v42, 16, v18
	v_and_b32_e32 v30, 0xffff0000, v30
	v_and_b32_e32 v43, 0xffff0000, v18
	v_sub_f32_e32 v18, v42, v1
	v_lshlrev_b32_e32 v44, 16, v26
	v_mul_f32_e32 v18, v18, v44
	v_sub_f32_e32 v44, v43, v30
	v_and_b32_e32 v26, 0xffff0000, v26
	v_lshl_add_u64 v[68:69], v[66:67], 0, s[16:17]
	v_mul_f32_e32 v26, v44, v26
	v_lshl_add_u64 v[72:73], v[70:71], 0, s[16:17]
	global_store_dwordx4 v[68:69], v[34:37], off offset:16 nt
	global_store_dwordx4 v[72:73], v[38:41], off offset:16 nt
	v_cvt_pk_bf16_f32 v18, v18, v26
	v_add_f32_e32 v1, v1, v42
	v_lshlrev_b32_e32 v26, 16, v22
	v_mul_f32_e32 v1, v1, v26
	v_add_f32_e32 v26, v30, v43
	v_and_b32_e32 v22, 0xffff0000, v22
	v_mul_f32_e32 v22, v26, v22
	v_cvt_pk_bf16_f32 v22, v1, v22
	v_lshlrev_b32_e32 v1, 16, v31
	v_lshlrev_b32_e32 v26, 16, v19
	v_and_b32_e32 v30, 0xffff0000, v31
	v_and_b32_e32 v31, 0xffff0000, v19
	v_sub_f32_e32 v19, v26, v1
	v_add_f32_e32 v1, v1, v26
	v_lshlrev_b32_e32 v26, 16, v23
	v_lshlrev_b32_e32 v42, 16, v27
	v_mul_f32_e32 v1, v1, v26
	v_add_f32_e32 v26, v30, v31
	v_and_b32_e32 v23, 0xffff0000, v23
	v_mul_f32_e32 v19, v19, v42
	v_sub_f32_e32 v42, v31, v30
	v_and_b32_e32 v27, 0xffff0000, v27
	v_mul_f32_e32 v23, v26, v23
	v_mul_f32_e32 v27, v42, v27
	v_cvt_pk_bf16_f32 v19, v19, v27
	v_cvt_pk_bf16_f32 v23, v1, v23
	v_lshlrev_b32_e32 v1, 16, v32
	v_lshlrev_b32_e32 v26, 16, v20
	v_and_b32_e32 v27, 0xffff0000, v32
	v_and_b32_e32 v30, 0xffff0000, v20
	v_sub_f32_e32 v20, v26, v1
	v_add_f32_e32 v1, v1, v26
	v_lshlrev_b32_e32 v26, 16, v24
	v_lshlrev_b32_e32 v31, 16, v28
	v_mul_f32_e32 v1, v1, v26
	v_add_f32_e32 v26, v27, v30
	v_and_b32_e32 v24, 0xffff0000, v24
	v_mul_f32_e32 v20, v20, v31
	v_sub_f32_e32 v31, v30, v27
	v_and_b32_e32 v28, 0xffff0000, v28
	v_mul_f32_e32 v24, v26, v24
	s_add_u32 s0, s6, s18
	v_mul_f32_e32 v28, v31, v28
	v_cvt_pk_bf16_f32 v20, v20, v28
	v_cvt_pk_bf16_f32 v24, v1, v24
	v_lshlrev_b32_e32 v1, 16, v33
	v_lshlrev_b32_e32 v26, 16, v21
	s_addc_u32 s1, s7, s19
	v_and_b32_e32 v27, 0xffff0000, v33
	v_and_b32_e32 v28, 0xffff0000, v21
	v_sub_f32_e32 v21, v26, v1
	v_add_f32_e32 v1, v1, v26
	v_lshlrev_b32_e32 v26, 16, v25
	v_lshl_add_u64 v[34:35], s[0:1], 0, v[128:129]
	s_add_u32 s0, s6, s20
	v_mul_f32_e32 v1, v1, v26
	v_add_f32_e32 v26, v27, v28
	v_and_b32_e32 v25, 0xffff0000, v25
	s_addc_u32 s1, s7, s21
	v_lshlrev_b32_e32 v30, 16, v29
	v_mul_f32_e32 v25, v26, v25
	v_add_co_u32_e32 v26, vcc, s41, v34
	v_lshl_add_u64 v[38:39], s[0:1], 0, v[128:129]
	v_mul_f32_e32 v21, v21, v30
	v_sub_f32_e32 v30, v28, v27
	v_and_b32_e32 v29, 0xffff0000, v29
	v_addc_co_u32_e32 v27, vcc, 0, v35, vcc
	v_mul_f32_e32 v29, v30, v29
	v_cvt_pk_bf16_f32 v21, v21, v29
	v_cvt_pk_bf16_f32 v25, v1, v25
	global_store_dwordx4 v[26:27], v[18:21], off offset:2048 nt
	v_lshlrev_b32_e32 v1, 16, v14
	v_and_b32_e32 v14, 0xffff0000, v14
	v_add_co_u32_e32 v18, vcc, s41, v38
	v_lshlrev_b32_e32 v20, 16, v10
	s_nop 0
	v_addc_co_u32_e32 v19, vcc, 0, v39, vcc
	global_store_dwordx4 v[18:19], v[22:25], off offset:2048 nt
	v_lshlrev_b32_e32 v18, 16, v2
	v_and_b32_e32 v19, 0xffff0000, v2
	v_sub_f32_e32 v2, v18, v1
	v_mul_f32_e32 v2, v2, v20
	v_sub_f32_e32 v20, v19, v14
	v_and_b32_e32 v10, 0xffff0000, v10
	v_mul_f32_e32 v10, v20, v10
	v_cvt_pk_bf16_f32 v2, v2, v10
	v_add_f32_e32 v1, v1, v18
	s_waitcnt vmcnt(12)
	v_lshlrev_b32_e32 v10, 16, v6
	v_mul_f32_e32 v1, v1, v10
	v_add_f32_e32 v10, v14, v19
	v_and_b32_e32 v6, 0xffff0000, v6
	v_mul_f32_e32 v6, v10, v6
	v_cvt_pk_bf16_f32 v6, v1, v6
	v_lshlrev_b32_e32 v1, 16, v15
	v_lshlrev_b32_e32 v10, 16, v3
	v_and_b32_e32 v14, 0xffff0000, v15
	v_and_b32_e32 v15, 0xffff0000, v3
	v_sub_f32_e32 v3, v10, v1
	v_add_f32_e32 v1, v1, v10
	v_lshlrev_b32_e32 v10, 16, v7
	v_lshlrev_b32_e32 v18, 16, v11
	v_mul_f32_e32 v1, v1, v10
	v_add_f32_e32 v10, v14, v15
	v_and_b32_e32 v7, 0xffff0000, v7
	v_mul_f32_e32 v3, v3, v18
	v_sub_f32_e32 v18, v15, v14
	v_and_b32_e32 v11, 0xffff0000, v11
	v_mul_f32_e32 v7, v10, v7
	v_mul_f32_e32 v11, v18, v11
	v_cvt_pk_bf16_f32 v3, v3, v11
	v_cvt_pk_bf16_f32 v7, v1, v7
	v_lshlrev_b32_e32 v1, 16, v16
	v_lshlrev_b32_e32 v10, 16, v4
	v_and_b32_e32 v11, 0xffff0000, v16
	v_and_b32_e32 v14, 0xffff0000, v4
	v_sub_f32_e32 v4, v10, v1
	v_add_f32_e32 v1, v1, v10
	v_lshlrev_b32_e32 v10, 16, v8
	v_lshlrev_b32_e32 v15, 16, v12
	v_mul_f32_e32 v1, v1, v10
	v_add_f32_e32 v10, v11, v14
	v_and_b32_e32 v8, 0xffff0000, v8
	v_mul_f32_e32 v4, v4, v15
	v_sub_f32_e32 v15, v14, v11
	v_and_b32_e32 v12, 0xffff0000, v12
	v_mul_f32_e32 v8, v10, v8
	v_mul_f32_e32 v12, v15, v12
	v_cvt_pk_bf16_f32 v4, v4, v12
	v_cvt_pk_bf16_f32 v8, v1, v8
	v_lshlrev_b32_e32 v1, 16, v17
	v_lshlrev_b32_e32 v10, 16, v5
	v_and_b32_e32 v11, 0xffff0000, v17
	v_and_b32_e32 v12, 0xffff0000, v5
	v_sub_f32_e32 v5, v10, v1
	v_add_f32_e32 v1, v1, v10
	v_lshlrev_b32_e32 v10, 16, v9
	v_lshlrev_b32_e32 v14, 16, v13
	v_mul_f32_e32 v1, v1, v10
	v_add_f32_e32 v10, v11, v12
	v_and_b32_e32 v9, 0xffff0000, v9
	s_add_i32 s42, s42, s37
	s_add_i32 s38, s38, s39
	v_lshl_add_u64 v[36:37], v[34:35], 0, s[16:17]
	v_lshl_add_u64 v[40:41], v[38:39], 0, s[16:17]
	v_mul_f32_e32 v5, v5, v14
	v_sub_f32_e32 v14, v12, v11
	v_and_b32_e32 v13, 0xffff0000, v13
	v_mul_f32_e32 v9, v10, v9
	s_cmpk_gt_i32 s42, 0x7ff
	v_mul_f32_e32 v13, v14, v13
	v_cvt_pk_bf16_f32 v5, v5, v13
	v_cvt_pk_bf16_f32 v9, v1, v9
	global_store_dwordx4 v[36:37], v[2:5], off offset:16 nt
	global_store_dwordx4 v[40:41], v[6:9], off offset:16 nt
	s_cbranch_scc1 .LBB0_1654
.LBB0_1650:
	s_and_b32 s0, s42, 0xfffffc00
	s_ashr_i32 s1, s0, 31
	s_ashr_i32 s44, s42, 10
	s_and_b32 s46, s38, 0xffc
	s_lshl_b64 s[18:19], s[0:1], 1
	s_cmp_lg_u32 s46, 0
	s_cselect_b64 s[26:27], -1, 0
	s_sub_i32 s45, 0x2000, s46
	s_cmp_eq_u32 s46, 0
	s_cselect_b64 s[0:1], -1, 0
	s_and_b64 s[0:1], s[0:1], exec
	s_waitcnt vmcnt(0)
	v_lshl_add_u64 v[2:3], v[130:131], 0, s[18:19]
	s_cselect_b32 s22, 0, s45
	s_lshl_b32 s12, s46, 12
	v_lshl_add_u64 v[4:5], v[2:3], 0, s[12:13]
	s_add_u32 s12, s10, s12
	s_addc_u32 s21, s11, 0
	s_add_u32 s20, s12, s18
	s_mul_hi_i32 s43, s44, 0x2100
	s_mulk_i32 s44, 0x2100
	s_addc_u32 s21, s21, s19
	v_lshl_add_u64 v[6:7], s[20:21], 0, v[128:129]
	s_add_u32 s20, s44, s46
	s_addc_u32 s21, s43, 0
	s_lshl_b64 s[34:35], s[20:21], 13
	s_add_u32 s20, s8, s34
	s_addc_u32 s21, s9, s35
	v_lshl_add_u64 v[10:11], s[20:21], 0, v[128:129]
	s_add_u32 s20, s44, s22
	s_addc_u32 s21, s43, 0
	s_lshl_b64 s[20:21], s[20:21], 13
	global_load_dwordx4 v[98:101], v[4:5], off offset:16 nt
	global_load_dwordx4 v[114:117], v[4:5], off nt
	v_add_co_u32_e32 v4, vcc, s40, v6
	s_add_u32 s20, s8, s20
	s_nop 0
	v_addc_co_u32_e32 v5, vcc, 0, v7, vcc
	v_lshl_add_u64 v[8:9], v[6:7], 0, s[14:15]
	s_addc_u32 s21, s9, s21
	v_add_co_u32_e32 v6, vcc, s41, v10
	v_lshl_add_u64 v[14:15], s[20:21], 0, v[128:129]
	s_nop 0
	v_addc_co_u32_e32 v7, vcc, 0, v11, vcc
	s_or_b32 s22, s46, 1
	v_lshl_add_u64 v[12:13], v[10:11], 0, s[16:17]
	global_load_dwordx4 v[110:113], v[8:9], off offset:16 nt
	global_load_dwordx4 v[106:109], v[12:13], off offset:16 nt
	v_add_co_u32_e32 v8, vcc, s41, v14
	s_sub_i32 s23, 0x2000, s22
	s_lshl_b32 s12, s22, 12
	v_lshl_add_u64 v[16:17], v[14:15], 0, s[16:17]
	v_addc_co_u32_e32 v9, vcc, 0, v15, vcc
	global_load_dwordx4 v[122:125], v[6:7], off offset:2048 nt
	global_load_dwordx4 v[118:121], v[8:9], off offset:2048 nt
	global_load_dwordx4 v[136:139], v[4:5], off nt
	global_load_dwordx4 v[102:105], v[16:17], off offset:16 nt
	v_lshl_add_u64 v[4:5], v[2:3], 0, s[12:13]
	s_add_u32 s12, s10, s12
	s_addc_u32 s21, s11, 0
	s_add_u32 s20, s12, s18
	s_addc_u32 s21, s21, s19
	v_lshl_add_u64 v[6:7], s[20:21], 0, v[128:129]
	s_add_u32 s20, s44, s22
	s_addc_u32 s21, s43, 0
	s_lshl_b64 s[28:29], s[20:21], 13
	s_add_u32 s20, s8, s28
	s_addc_u32 s21, s9, s29
	v_lshl_add_u64 v[10:11], s[20:21], 0, v[128:129]
	s_add_u32 s20, s44, s23
	s_addc_u32 s21, s43, 0
	s_lshl_b64 s[30:31], s[20:21], 13
	global_load_dwordx4 v[66:69], v[4:5], off offset:16 nt
	global_load_dwordx4 v[82:85], v[4:5], off nt
	v_add_co_u32_e32 v4, vcc, s40, v6
	s_add_u32 s20, s8, s30
	s_nop 0
	v_addc_co_u32_e32 v5, vcc, 0, v7, vcc
	v_lshl_add_u64 v[8:9], v[6:7], 0, s[14:15]
	s_addc_u32 s21, s9, s31
	v_add_co_u32_e32 v6, vcc, s41, v10
	v_lshl_add_u64 v[14:15], s[20:21], 0, v[128:129]
	s_nop 0
	v_addc_co_u32_e32 v7, vcc, 0, v11, vcc
	s_or_b32 s22, s46, 2
	v_lshl_add_u64 v[12:13], v[10:11], 0, s[16:17]
	global_load_dwordx4 v[78:81], v[8:9], off offset:16 nt
	global_load_dwordx4 v[74:77], v[12:13], off offset:16 nt
	v_add_co_u32_e32 v8, vcc, s41, v14
	s_sub_i32 s24, 0x2000, s22
	s_lshl_b32 s12, s22, 12
	v_lshl_add_u64 v[16:17], v[14:15], 0, s[16:17]
	v_addc_co_u32_e32 v9, vcc, 0, v15, vcc
	global_load_dwordx4 v[90:93], v[6:7], off offset:2048 nt
	global_load_dwordx4 v[86:89], v[8:9], off offset:2048 nt
	global_load_dwordx4 v[94:97], v[4:5], off nt
	global_load_dwordx4 v[70:73], v[16:17], off offset:16 nt
	v_lshl_add_u64 v[4:5], v[2:3], 0, s[12:13]
	s_add_u32 s12, s10, s12
	s_addc_u32 s21, s11, 0
	s_add_u32 s20, s12, s18
	s_addc_u32 s21, s21, s19
	v_lshl_add_u64 v[6:7], s[20:21], 0, v[128:129]
	s_add_u32 s20, s44, s22
	s_addc_u32 s21, s43, 0
	s_lshl_b64 s[22:23], s[20:21], 13
	s_add_u32 s20, s8, s22
	s_addc_u32 s21, s9, s23
	v_lshl_add_u64 v[10:11], s[20:21], 0, v[128:129]
	s_add_u32 s20, s44, s24
	s_addc_u32 s21, s43, 0
	s_lshl_b64 s[24:25], s[20:21], 13
	global_load_dwordx4 v[34:37], v[4:5], off offset:16 nt
	global_load_dwordx4 v[50:53], v[4:5], off nt
	v_add_co_u32_e32 v4, vcc, s40, v6
	s_add_u32 s20, s8, s24
	s_nop 0
	v_addc_co_u32_e32 v5, vcc, 0, v7, vcc
	v_lshl_add_u64 v[8:9], v[6:7], 0, s[14:15]
	s_addc_u32 s21, s9, s25
	v_add_co_u32_e32 v6, vcc, s41, v10
	v_lshl_add_u64 v[14:15], s[20:21], 0, v[128:129]
	s_nop 0
	v_addc_co_u32_e32 v7, vcc, 0, v11, vcc
	s_or_b32 s20, s46, 3
	v_lshl_add_u64 v[12:13], v[10:11], 0, s[16:17]
	global_load_dwordx4 v[46:49], v[8:9], off offset:16 nt
	global_load_dwordx4 v[42:45], v[12:13], off offset:16 nt
	v_add_co_u32_e32 v8, vcc, s41, v14
	s_sub_i32 s46, 0x2000, s20
	s_lshl_b32 s12, s20, 12
	v_lshl_add_u64 v[16:17], v[14:15], 0, s[16:17]
	v_addc_co_u32_e32 v9, vcc, 0, v15, vcc
	global_load_dwordx4 v[58:61], v[6:7], off offset:2048 nt
	global_load_dwordx4 v[54:57], v[8:9], off offset:2048 nt
	global_load_dwordx4 v[62:65], v[4:5], off nt
	global_load_dwordx4 v[38:41], v[16:17], off offset:16 nt
	v_lshl_add_u64 v[6:7], v[2:3], 0, s[12:13]
	s_add_u32 s12, s10, s12
	s_addc_u32 s21, s11, 0
	s_add_u32 s18, s12, s18
	s_addc_u32 s19, s21, s19
	v_lshl_add_u64 v[8:9], s[18:19], 0, v[128:129]
	s_add_u32 s18, s44, s20
	s_addc_u32 s19, s43, 0
	s_lshl_b64 s[18:19], s[18:19], 13
	s_add_u32 s20, s8, s18
	s_addc_u32 s21, s9, s19
	v_lshl_add_u64 v[12:13], s[20:21], 0, v[128:129]
	s_add_u32 s20, s44, s46
	s_addc_u32 s21, s43, 0
	s_lshl_b64 s[20:21], s[20:21], 13
	global_load_dwordx4 v[2:5], v[6:7], off offset:16 nt
	global_load_dwordx4 v[18:21], v[6:7], off nt
	v_add_co_u32_e32 v6, vcc, s40, v8
	s_add_u32 s46, s8, s20
	s_nop 0
	v_addc_co_u32_e32 v7, vcc, 0, v9, vcc
	v_lshl_add_u64 v[10:11], v[8:9], 0, s[14:15]
	s_addc_u32 s47, s9, s21
	v_add_co_u32_e32 v8, vcc, s41, v12
	v_lshl_add_u64 v[22:23], v[12:13], 0, s[16:17]
	v_lshl_add_u64 v[24:25], s[46:47], 0, v[128:129]
	v_addc_co_u32_e32 v9, vcc, 0, v13, vcc
	global_load_dwordx4 v[14:17], v[10:11], off offset:16 nt
	s_nop 0
	global_load_dwordx4 v[10:13], v[22:23], off offset:16 nt
	v_add_co_u32_e32 v22, vcc, s41, v24
	v_lshl_add_u64 v[132:133], v[24:25], 0, s[16:17]
	s_nop 0
	v_addc_co_u32_e32 v23, vcc, 0, v25, vcc
	global_load_dwordx4 v[26:29], v[8:9], off offset:2048 nt
	s_nop 0
	global_load_dwordx4 v[22:25], v[22:23], off offset:2048 nt
	s_nop 0
	global_load_dwordx4 v[30:33], v[6:7], off nt
	s_nop 0
	global_load_dwordx4 v[6:9], v[132:133], off offset:16 nt
	s_waitcnt vmcnt(25)
	v_lshlrev_b32_e32 v1, 16, v136
	v_lshlrev_b32_e32 v127, 16, v114
	v_and_b32_e32 v136, 0xffff0000, v136
	v_and_b32_e32 v114, 0xffff0000, v114
	v_sub_f32_e32 v140, v127, v1
	v_lshlrev_b32_e32 v141, 16, v122
	v_mul_f32_e32 v140, v140, v141
	v_sub_f32_e32 v141, v114, v136
	v_and_b32_e32 v122, 0xffff0000, v122
	v_add_f32_e32 v1, v1, v127
	v_lshlrev_b32_e32 v127, 16, v118
	v_add_f32_e32 v114, v136, v114
	v_and_b32_e32 v118, 0xffff0000, v118
	v_mul_f32_e32 v122, v141, v122
	v_mul_f32_e32 v1, v1, v127
	v_mul_f32_e32 v114, v114, v118
	v_cvt_pk_bf16_f32 v122, v140, v122
	v_cvt_pk_bf16_f32 v114, v1, v114
	v_lshlrev_b32_e32 v1, 16, v137
	v_lshlrev_b32_e32 v118, 16, v115
	v_and_b32_e32 v127, 0xffff0000, v137
	v_and_b32_e32 v115, 0xffff0000, v115
	v_sub_f32_e32 v136, v118, v1
	v_lshlrev_b32_e32 v137, 16, v123
	v_add_f32_e32 v1, v1, v118
	v_lshlrev_b32_e32 v118, 16, v119
	v_mul_f32_e32 v136, v136, v137
	v_sub_f32_e32 v137, v115, v127
	v_and_b32_e32 v123, 0xffff0000, v123
	v_mul_f32_e32 v1, v1, v118
	v_add_f32_e32 v115, v127, v115
	v_and_b32_e32 v118, 0xffff0000, v119
	v_mul_f32_e32 v123, v137, v123
	v_mul_f32_e32 v115, v115, v118
	v_cvt_pk_bf16_f32 v123, v136, v123
	v_cvt_pk_bf16_f32 v115, v1, v115
	v_lshlrev_b32_e32 v1, 16, v138
	v_lshlrev_b32_e32 v118, 16, v116
	s_add_u32 s44, s44, s45
	v_and_b32_e32 v119, 0xffff0000, v138
	v_and_b32_e32 v116, 0xffff0000, v116
	v_sub_f32_e32 v127, v118, v1
	v_lshlrev_b32_e32 v136, 16, v124
	v_add_f32_e32 v1, v1, v118
	v_lshlrev_b32_e32 v118, 16, v120
	s_addc_u32 s45, s43, 0
	v_mul_f32_e32 v127, v127, v136
	v_sub_f32_e32 v136, v116, v119
	v_and_b32_e32 v124, 0xffff0000, v124
	v_mul_f32_e32 v1, v1, v118
	v_add_f32_e32 v116, v119, v116
	v_and_b32_e32 v118, 0xffff0000, v120
	s_add_u32 s34, s6, s34
	v_mul_f32_e32 v124, v136, v124
	v_mul_f32_e32 v116, v116, v118
	s_addc_u32 s35, s7, s35
	v_cvt_pk_bf16_f32 v124, v127, v124
	v_cvt_pk_bf16_f32 v116, v1, v116
	v_lshlrev_b32_e32 v1, 16, v139
	v_lshlrev_b32_e32 v118, 16, v117
	v_lshl_add_u64 v[134:135], s[34:35], 0, v[128:129]
	s_lshl_b64 s[34:35], s[44:45], 13
	v_and_b32_e32 v119, 0xffff0000, v139
	v_and_b32_e32 v117, 0xffff0000, v117
	v_sub_f32_e32 v120, v118, v1
	v_lshlrev_b32_e32 v127, 16, v125
	v_add_f32_e32 v1, v1, v118
	v_lshlrev_b32_e32 v118, 16, v121
	s_add_u32 s34, s6, s34
	v_mul_f32_e32 v120, v120, v127
	v_sub_f32_e32 v127, v117, v119
	v_mul_f32_e32 v1, v1, v118
	v_add_f32_e32 v117, v119, v117
	v_and_b32_e32 v118, 0xffff0000, v121
	s_addc_u32 s35, s7, s35
	v_mul_f32_e32 v117, v117, v118
	v_add_co_u32_e32 v118, vcc, 0x1000, v134
	v_lshl_add_u64 v[132:133], s[34:35], 0, v[128:129]
	v_and_b32_e32 v125, 0xffff0000, v125
	v_addc_co_u32_e32 v119, vcc, 0, v135, vcc
	v_lshl_add_u64 v[132:133], v[132:133], 0, s[16:17]
	v_mul_f32_e32 v125, v127, v125
	s_mov_b64 vcc, s[0:1]
	v_cvt_pk_bf16_f32 v125, v120, v125
	v_cvt_pk_bf16_f32 v117, v1, v117
	global_store_dwordx4 v[118:119], v[122:125], off offset:2048 nt
	s_cbranch_vccnz .LBB0_1652
	global_store_dwordx4 v[132:133], v[114:117], off nt
.LBB0_1652:
	v_lshlrev_b32_e32 v1, 16, v110
	s_nop 0
	v_lshlrev_b32_e32 v116, 16, v98
	v_and_b32_e32 v110, 0xffff0000, v110
	v_and_b32_e32 v98, 0xffff0000, v98
	v_sub_f32_e32 v117, v116, v1
	v_lshlrev_b32_e32 v118, 16, v106
	v_mul_f32_e32 v117, v117, v118
	v_sub_f32_e32 v118, v98, v110
	v_and_b32_e32 v106, 0xffff0000, v106
	v_add_f32_e32 v1, v1, v116
	s_waitcnt vmcnt(25)
	v_lshlrev_b32_e32 v116, 16, v102
	v_add_f32_e32 v98, v110, v98
	v_and_b32_e32 v102, 0xffff0000, v102
	v_mul_f32_e32 v106, v118, v106
	v_mul_f32_e32 v1, v1, v116
	v_mul_f32_e32 v98, v98, v102
	v_cvt_pk_bf16_f32 v106, v117, v106
	v_cvt_pk_bf16_f32 v98, v1, v98
	v_lshlrev_b32_e32 v1, 16, v111
	v_lshlrev_b32_e32 v102, 16, v99
	v_and_b32_e32 v110, 0xffff0000, v111
	v_and_b32_e32 v99, 0xffff0000, v99
	v_sub_f32_e32 v111, v102, v1
	v_lshlrev_b32_e32 v116, 16, v107
	v_add_f32_e32 v1, v1, v102
	v_lshlrev_b32_e32 v102, 16, v103
	v_mul_f32_e32 v111, v111, v116
	v_sub_f32_e32 v116, v99, v110
	v_and_b32_e32 v107, 0xffff0000, v107
	v_mul_f32_e32 v1, v1, v102
	v_add_f32_e32 v99, v110, v99
	v_and_b32_e32 v102, 0xffff0000, v103
	v_mul_f32_e32 v107, v116, v107
	v_mul_f32_e32 v99, v99, v102
	v_cvt_pk_bf16_f32 v107, v111, v107
	v_cvt_pk_bf16_f32 v99, v1, v99
	v_lshlrev_b32_e32 v1, 16, v112
	v_lshlrev_b32_e32 v102, 16, v100
	v_and_b32_e32 v103, 0xffff0000, v112
	v_and_b32_e32 v100, 0xffff0000, v100
	v_sub_f32_e32 v110, v102, v1
	v_lshlrev_b32_e32 v111, 16, v108
	v_add_f32_e32 v1, v1, v102
	v_lshlrev_b32_e32 v102, 16, v104
	v_mul_f32_e32 v110, v110, v111
	v_sub_f32_e32 v111, v100, v103
	v_and_b32_e32 v108, 0xffff0000, v108
	v_mul_f32_e32 v1, v1, v102
	v_add_f32_e32 v100, v103, v100
	v_and_b32_e32 v102, 0xffff0000, v104
	v_mul_f32_e32 v108, v111, v108
	v_mul_f32_e32 v100, v100, v102
	v_cvt_pk_bf16_f32 v108, v110, v108
	v_cvt_pk_bf16_f32 v100, v1, v100
	v_lshlrev_b32_e32 v1, 16, v113
	v_lshlrev_b32_e32 v102, 16, v101
	v_and_b32_e32 v103, 0xffff0000, v113
	v_and_b32_e32 v101, 0xffff0000, v101
	v_sub_f32_e32 v104, v102, v1
	v_lshlrev_b32_e32 v110, 16, v109
	v_add_f32_e32 v1, v1, v102
	v_lshlrev_b32_e32 v102, 16, v105
	v_mul_f32_e32 v104, v104, v110
	v_sub_f32_e32 v110, v101, v103
	v_and_b32_e32 v109, 0xffff0000, v109
	v_mul_f32_e32 v1, v1, v102
	v_add_f32_e32 v101, v103, v101
	v_and_b32_e32 v102, 0xffff0000, v105
	v_lshl_add_u64 v[114:115], v[134:135], 0, s[16:17]
	v_mul_f32_e32 v109, v110, v109
	v_mul_f32_e32 v101, v101, v102
	s_andn2_b64 vcc, exec, s[26:27]
	v_cvt_pk_bf16_f32 v109, v104, v109
	v_cvt_pk_bf16_f32 v101, v1, v101
	global_store_dwordx4 v[114:115], v[106:109], off offset:16 nt
	s_cbranch_vccnz .LBB0_1649
	global_store_dwordx4 v[132:133], v[98:101], off offset:16 nt
	s_branch .LBB0_1649
.LBB0_1654:
	s_cmp_lt_i32 s36, 2
	s_cbranch_scc0 .LBB0_1656
	s_mul_i32 s1, s36, 0x2100000
	s_mul_hi_i32 s0, s36, 0x2100000
	s_add_u32 s1, s1, 0x1000c00
	s_addc_u32 s0, s0, 0
	s_waitcnt vmcnt(0)
	v_mov_b32_e32 v3, s0
	s_lshl_b32 s0, s36, 10
	v_or_b32_e32 v2, s1, v126
	s_ashr_i32 s1, s0, 31
	s_lshl_b64 s[0:1], s[0:1], 2
	s_add_u32 s0, s92, s0
	s_addc_u32 s1, s93, s1
	v_lshlrev_b32_e32 v6, 2, v126
	v_mov_b32_e32 v7, 0
	v_lshlrev_b64 v[14:15], 1, v[2:3]
	v_lshl_add_u64 v[10:11], s[0:1], 0, v[6:7]
	s_mov_b32 s0, 0x300000
	v_lshl_add_u64 v[16:17], s[8:9], 0, v[14:15]
	v_add_co_u32_e32 v6, vcc, s0, v10
	s_mov_b64 s[0:1], 0x300000
	global_load_dwordx4 v[2:5], v[16:17], off nt
	v_addc_co_u32_e32 v7, vcc, 0, v11, vcc
	v_lshl_add_u64 v[18:19], v[10:11], 0, s[0:1]
	global_load_dwordx4 v[6:9], v[6:7], off nt
	v_lshl_add_u64 v[14:15], s[6:7], 0, v[14:15]
	global_load_dwordx4 v[10:13], v[18:19], off offset:16 nt
	s_waitcnt vmcnt(2)
	v_lshlrev_b32_e32 v1, 16, v2
	v_and_b32_e32 v2, 0xffff0000, v2
	v_lshlrev_b32_e32 v20, 16, v3
	v_and_b32_e32 v3, 0xffff0000, v3
	v_lshlrev_b32_e32 v21, 16, v4
	v_and_b32_e32 v4, 0xffff0000, v4
	v_lshlrev_b32_e32 v22, 16, v5
	v_and_b32_e32 v5, 0xffff0000, v5
	s_waitcnt vmcnt(1)
	v_mul_f32_e32 v1, v6, v1
	v_mul_f32_e32 v2, v7, v2
	v_mul_f32_e32 v6, v8, v20
	v_mul_f32_e32 v3, v9, v3
	s_waitcnt vmcnt(0)
	v_mul_f32_e32 v7, v10, v21
	v_mul_f32_e32 v4, v11, v4
	v_mul_f32_e32 v8, v12, v22
	v_mul_f32_e32 v5, v13, v5
	v_cvt_pk_bf16_f32 v2, v1, v2
	v_cvt_pk_bf16_f32 v3, v6, v3
	v_cvt_pk_bf16_f32 v4, v7, v4
	v_cvt_pk_bf16_f32 v5, v8, v5
	global_load_dwordx4 v[6:9], v[16:17], off offset:16 nt
	s_waitcnt vmcnt(0)
	v_lshlrev_b32_e32 v1, 16, v6
	global_store_dwordx4 v[14:15], v[2:5], off nt
	global_load_dwordx4 v[2:5], v[18:19], off offset:32 nt
	s_nop 0
	global_load_dwordx4 v[10:13], v[18:19], off offset:48 nt
	v_and_b32_e32 v6, 0xffff0000, v6
	v_lshlrev_b32_e32 v16, 16, v7
	v_and_b32_e32 v7, 0xffff0000, v7
	v_lshlrev_b32_e32 v17, 16, v8
	v_and_b32_e32 v8, 0xffff0000, v8
	v_lshlrev_b32_e32 v18, 16, v9
	v_and_b32_e32 v9, 0xffff0000, v9
	s_waitcnt vmcnt(1)
	v_mul_f32_e32 v1, v2, v1
	v_mul_f32_e32 v2, v3, v6
	v_mul_f32_e32 v3, v4, v16
	v_mul_f32_e32 v4, v5, v7
	s_waitcnt vmcnt(0)
	v_mul_f32_e32 v5, v10, v17
	v_mul_f32_e32 v6, v11, v8
	v_mul_f32_e32 v7, v12, v18
	v_mul_f32_e32 v8, v13, v9
	v_cvt_pk_bf16_f32 v2, v1, v2
	v_cvt_pk_bf16_f32 v3, v3, v4
	v_cvt_pk_bf16_f32 v4, v5, v6
	v_cvt_pk_bf16_f32 v5, v7, v8
	global_store_dwordx4 v[14:15], v[2:5], off offset:16 nt
